# P5 chunk-staging block: single vmcnt(0) before 8 ds_write_b128 replaced by counted vmcnt(7..0) waits (strategy 1 on a spot not yet edited)
# speedup vs baseline: 1.0057x; 1.0057x over previous
; #define LAS __attribute__((address_space(3)))
; #define SYNC() __syncthreads()
; __device__ __forceinline__ void vt_unit(const Args& a, LAS unsigned char* lds, int tv) {
;     ...
;     const size_t r0 = (size_t)tv * 64; const int b = tv >> 8, s0 = (tv & 255) * 64;
; #pragma unroll
;     for (int i = 0; i < 8; ++i) { const int id = tid + 512 * i, row = id >> 6, ch = id & 63;
;         *(LAS u32x4*)(T + row * 520 + 8 * ch) = *(const u32x4*)(proj + (r0 + row) * NIN + 1024 + 8 * ch); }
;     SYNC();
.LBB0_385:
	s_add_i32 s2, s60, 0xfffff800
	s_lshl_b32 s3, s2, 6
	v_or_b32_e32 v2, s3, v109
	v_mul_lo_u32 v106, v2, s59
	v_lshl_add_u64 v[2:3], v[106:107], 1, s[86:87]
	v_mov_b32_e32 v119, v107
	v_or_b32_e32 v4, s3, v111
	v_lshl_add_u64 v[2:3], v[2:3], 0, v[118:119]
	v_mul_lo_u32 v106, v4, s59
	v_add_co_u32_e32 v2, vcc, 0x7000000, v2
	v_lshl_add_u64 v[4:5], v[106:107], 1, s[86:87]
	v_or_b32_e32 v10, s3, v113
	v_addc_co_u32_e32 v3, vcc, 0, v3, vcc
	v_lshl_add_u64 v[4:5], v[4:5], 0, v[118:119]
	v_mul_lo_u32 v106, v10, s59
	v_add_co_u32_e32 v6, vcc, 0x7000000, v4
	v_lshl_add_u64 v[10:11], v[106:107], 1, s[86:87]
	v_or_b32_e32 v12, s3, v140
	v_addc_co_u32_e32 v7, vcc, 0, v5, vcc
	v_lshl_add_u64 v[10:11], v[10:11], 0, v[118:119]
	v_mul_lo_u32 v106, v12, s59
	v_add_co_u32_e32 v10, vcc, 0x7000000, v10
	v_lshl_add_u64 v[12:13], v[106:107], 1, s[86:87]
	v_or_b32_e32 v18, s3, v141
	v_addc_co_u32_e32 v11, vcc, 0, v11, vcc
	v_lshl_add_u64 v[12:13], v[12:13], 0, v[118:119]
	v_mul_lo_u32 v106, v18, s59
	v_add_co_u32_e32 v14, vcc, 0x7000000, v12
	v_lshl_add_u64 v[18:19], v[106:107], 1, s[86:87]
	v_or_b32_e32 v20, s3, v142
	v_addc_co_u32_e32 v15, vcc, 0, v13, vcc
	v_lshl_add_u64 v[18:19], v[18:19], 0, v[118:119]
	v_mul_lo_u32 v106, v20, s59
	v_add_co_u32_e32 v18, vcc, 0x7000000, v18
	v_lshl_add_u64 v[20:21], v[106:107], 1, s[86:87]
	v_or_b32_e32 v26, s3, v143
	v_addc_co_u32_e32 v19, vcc, 0, v19, vcc
	v_lshl_add_u64 v[20:21], v[20:21], 0, v[118:119]
	v_mul_lo_u32 v106, v26, s59
	v_add_co_u32_e32 v22, vcc, 0x7000000, v20
	v_lshl_add_u64 v[26:27], v[106:107], 1, s[86:87]
	v_or_b32_e32 v28, s3, v144
	v_addc_co_u32_e32 v23, vcc, 0, v21, vcc
	v_lshl_add_u64 v[26:27], v[26:27], 0, v[118:119]
	v_mul_lo_u32 v106, v28, s59
	v_add_co_u32_e32 v26, vcc, 0x7000000, v26
	v_lshl_add_u64 v[28:29], v[106:107], 1, s[86:87]
	s_nop 0
	v_addc_co_u32_e32 v27, vcc, 0, v27, vcc
	v_lshl_add_u64 v[28:29], v[28:29], 0, v[118:119]
	v_add_co_u32_e32 v30, vcc, 0x7000000, v28
	global_load_dwordx4 v[2:5], v[2:3], off offset:2048
	s_nop 0
	global_load_dwordx4 v[6:9], v[6:7], off offset:2048
	v_addc_co_u32_e32 v31, vcc, 0, v29, vcc
	global_load_dwordx4 v[10:13], v[10:11], off offset:2048
	s_nop 0
	global_load_dwordx4 v[14:17], v[14:15], off offset:2048
	s_nop 0
	global_load_dwordx4 v[18:21], v[18:19], off offset:2048
	s_nop 0
	global_load_dwordx4 v[22:25], v[22:23], off offset:2048
	s_nop 0
	global_load_dwordx4 v[26:29], v[26:27], off offset:2048
	s_nop 0
	global_load_dwordx4 v[30:33], v[30:31], off offset:2048
	s_lshl_b32 s3, s2, 1
	s_and_b32 s3, s3, 0x200
	s_lshl_b32 s2, s2, 7
	s_and_b32 s22, s2, 0x7f80
	s_waitcnt vmcnt(7)
	ds_write_b128 v151, v[2:5]
	s_waitcnt vmcnt(6)
	ds_write_b128 v152, v[6:9]
	s_waitcnt vmcnt(5)
	ds_write_b128 v151, v[10:13] offset:16640
	s_waitcnt vmcnt(4)
	ds_write_b128 v153, v[14:17]
	s_waitcnt vmcnt(3)
	ds_write_b128 v151, v[18:21] offset:33280
	s_waitcnt vmcnt(2)
	ds_write_b128 v154, v[22:25]
	s_waitcnt vmcnt(1)
	ds_write_b128 v151, v[26:29] offset:49920
	s_waitcnt vmcnt(0)
	ds_write_b128 v155, v[30:33]
	s_waitcnt lgkmcnt(0)
	s_barrier
; #define SYNC() __syncthreads()
; __device__ __forceinline__ void vt_unit(const Args& a, LAS unsigned char* lds, int tv) {
;     ...
;     { const int h = tid >> 7, d = tid & 127;
;       bf16_t* dst = (bf16_t*)(a.ws + WS_VT) + ((size_t)(b * 4 + h) * 128 + d) * VSTR + s0;
; #pragma unroll
;       for (int i = 0; i < 8; ++i) { unsigned w[4];
; #pragma unroll
;           for (int e = 0; e < 4; ++e) { const int k0 = 16 * (i >> 1) + 4 * (i & 1) + ((2 * e) & 3) + 8 * (e >> 1);
;               w[e] = (unsigned)T[k0 * 520 + tid] | ((unsigned)T[(k0 + 1) * 520 + tid] << 16); }
;           *(u32x4*)(dst + 8 * i) = (u32x4){w[0], w[1], w[2], w[3]}; } }
;     SYNC();
	v_add_u32_e32 v2, s3, v1
	s_movk_i32 s3, 0x780
	ds_read_u16 v4, v146
	ds_read_u16 v5, v146 offset:1040
	ds_read_u16 v6, v146 offset:2080
	ds_read_u16 v7, v146 offset:3120
	ds_read_u16 v8, v146 offset:4160
	ds_read_u16 v9, v146 offset:5200
	ds_read_u16 v10, v146 offset:6240
	ds_read_u16 v11, v146 offset:7280
	v_and_or_b32 v2, v2, s3, v145
	s_waitcnt lgkmcnt(6)
	v_lshl_or_b32 v4, v5, 16, v4
	s_waitcnt lgkmcnt(4)
	v_lshl_or_b32 v5, v7, 16, v6
	ds_read_u16 v6, v146 offset:8320
	ds_read_u16 v7, v146 offset:9360
	ds_read_u16 v12, v146 offset:10400
	ds_read_u16 v13, v146 offset:11440
	ds_read_u16 v14, v146 offset:12480
	ds_read_u16 v15, v146 offset:13520
	ds_read_u16 v16, v146 offset:14560
	ds_read_u16 v17, v146 offset:15600
	v_mul_u32_u24_e32 v2, 0x4040, v2
	v_lshlrev_b32_e32 v106, 1, v2
	v_lshl_add_u64 v[2:3], s[28:29], 0, v[106:107]
	v_lshl_add_u64 v[2:3], v[2:3], 0, s[22:23]
	s_waitcnt lgkmcnt(6)
	v_lshl_or_b32 v6, v7, 16, v6
	s_waitcnt lgkmcnt(4)
	v_lshl_or_b32 v7, v13, 16, v12
	global_store_dwordx4 v[2:3], v[4:7], off
	s_nop 1
	v_lshl_or_b32 v4, v9, 16, v8
	v_lshl_or_b32 v5, v11, 16, v10
	s_waitcnt lgkmcnt(2)
	v_lshl_or_b32 v6, v15, 16, v14
	s_waitcnt lgkmcnt(0)
	v_lshl_or_b32 v7, v17, 16, v16
	global_store_dwordx4 v[2:3], v[4:7], off offset:16
	ds_read_u16 v4, v146 offset:16640
	ds_read_u16 v5, v146 offset:17680
	ds_read_u16 v6, v146 offset:18720
	ds_read_u16 v7, v146 offset:19760
	ds_read_u16 v8, v146 offset:20800
	ds_read_u16 v9, v146 offset:21840
	ds_read_u16 v10, v146 offset:22880
	ds_read_u16 v11, v146 offset:23920
	s_waitcnt lgkmcnt(6)
	v_lshl_or_b32 v4, v5, 16, v4
	s_waitcnt lgkmcnt(4)
	v_lshl_or_b32 v5, v7, 16, v6
	ds_read_u16 v6, v146 offset:24960
	ds_read_u16 v7, v146 offset:26000
	ds_read_u16 v12, v146 offset:27040
	ds_read_u16 v13, v146 offset:28080
	ds_read_u16 v14, v146 offset:29120
	ds_read_u16 v15, v146 offset:30160
	ds_read_u16 v16, v146 offset:31200
	ds_read_u16 v17, v146 offset:32240
	s_waitcnt lgkmcnt(6)
	v_lshl_or_b32 v6, v7, 16, v6
	s_waitcnt lgkmcnt(4)
	v_lshl_or_b32 v7, v13, 16, v12
	global_store_dwordx4 v[2:3], v[4:7], off offset:32
	s_nop 1
	v_lshl_or_b32 v4, v9, 16, v8
	v_lshl_or_b32 v5, v11, 16, v10
	s_waitcnt lgkmcnt(2)
	v_lshl_or_b32 v6, v15, 16, v14
	s_waitcnt lgkmcnt(0)
	v_lshl_or_b32 v7, v17, 16, v16
	global_store_dwordx4 v[2:3], v[4:7], off offset:48
	ds_read_u16 v4, v146 offset:33280
	ds_read_u16 v5, v146 offset:34320
	ds_read_u16 v6, v146 offset:35360
	ds_read_u16 v7, v146 offset:36400
	ds_read_u16 v8, v146 offset:37440
	ds_read_u16 v9, v146 offset:38480
	ds_read_u16 v10, v146 offset:39520
	ds_read_u16 v11, v146 offset:40560
	s_waitcnt lgkmcnt(6)
	v_lshl_or_b32 v4, v5, 16, v4
	s_waitcnt lgkmcnt(4)
	v_lshl_or_b32 v5, v7, 16, v6
	ds_read_u16 v6, v146 offset:41600
	ds_read_u16 v7, v146 offset:42640
	ds_read_u16 v12, v146 offset:43680
	ds_read_u16 v13, v146 offset:44720
	ds_read_u16 v14, v146 offset:45760
	ds_read_u16 v15, v146 offset:46800
	ds_read_u16 v16, v146 offset:47840
	ds_read_u16 v17, v146 offset:48880
	s_waitcnt lgkmcnt(6)
	v_lshl_or_b32 v6, v7, 16, v6
	s_waitcnt lgkmcnt(4)
	v_lshl_or_b32 v7, v13, 16, v12
	global_store_dwordx4 v[2:3], v[4:7], off offset:64
	s_nop 1
	v_lshl_or_b32 v4, v9, 16, v8
	v_lshl_or_b32 v5, v11, 16, v10
	s_waitcnt lgkmcnt(2)
	v_lshl_or_b32 v6, v15, 16, v14
	s_waitcnt lgkmcnt(0)
	v_lshl_or_b32 v7, v17, 16, v16
	global_store_dwordx4 v[2:3], v[4:7], off offset:80
	ds_read_u16 v4, v146 offset:49920
	ds_read_u16 v5, v146 offset:50960
	ds_read_u16 v6, v146 offset:52000
	ds_read_u16 v7, v146 offset:53040
	ds_read_u16 v8, v146 offset:54080
	ds_read_u16 v9, v146 offset:55120
	ds_read_u16 v10, v146 offset:56160
	ds_read_u16 v11, v146 offset:57200
	s_waitcnt lgkmcnt(6)
	v_lshl_or_b32 v4, v5, 16, v4
	s_waitcnt lgkmcnt(4)
	v_lshl_or_b32 v5, v7, 16, v6
	ds_read_u16 v6, v146 offset:58240
	ds_read_u16 v7, v146 offset:59280
	ds_read_u16 v12, v146 offset:60320
	ds_read_u16 v13, v146 offset:61360
	ds_read_u16 v14, v146 offset:62400
	ds_read_u16 v15, v146 offset:63440
	ds_read_u16 v16, v146 offset:64480
	ds_read_u16 v17, v146 offset:65520
	s_waitcnt lgkmcnt(6)
	v_lshl_or_b32 v6, v7, 16, v6
	s_waitcnt lgkmcnt(4)
	v_lshl_or_b32 v7, v13, 16, v12
	global_store_dwordx4 v[2:3], v[4:7], off offset:96
	s_nop 1
	v_lshl_or_b32 v4, v9, 16, v8
	v_lshl_or_b32 v5, v11, 16, v10
	s_waitcnt lgkmcnt(2)
	v_lshl_or_b32 v6, v15, 16, v14
	s_waitcnt lgkmcnt(0)
	v_lshl_or_b32 v7, v17, 16, v16
	global_store_dwordx4 v[2:3], v[4:7], off offset:112
	s_barrier
	s_cbranch_execnz .LBB0_382
